# scan prefetch depth 8 (was 4) on top of GLA3 state-load prefetch, xattn/mixerC XCD remap, EpiResid hoist
# speedup vs baseline: 1.0030x; 1.0030x over previous
.LBB0_555:
	v_ashrrev_i32_e32 v0, 17, v28
	s_mov_b32 s7, 0x20000
	v_ashrrev_i32_e32 v1, 31, v0
	v_cmp_gt_u32_e32 vcc, s7, v28
	v_lshlrev_b64 v[10:11], 10, v[0:1]
	v_lshrrev_b32_e32 v0, 7, v28
	s_movk_i32 s7, 0x3e0
	v_and_or_b32 v10, v0, s7, v10
	v_lshlrev_b32_e32 v0, 4, v28
	v_and_b32_e32 v8, 0xfff0, v0
	v_lshlrev_b32_e32 v0, 5, v28
	v_lshl_add_u64 v[12:13], s[46:47], 0, v[8:9]
	v_and_b32_e32 v8, 0x1e0, v0
	v_lshl_add_u64 v[14:15], s[14:15], 0, v[8:9]
	v_mov_b32_e32 v40, 31
	v_cndmask_b32_e32 v8, v40, v9, vcc
	v_lshl_add_u64 v[40:41], v[10:11], 0, v[8:9]
	v_lshlrev_b64 v[42:43], 16, v[40:41]
	v_lshl_add_u64 v[42:43], v[12:13], 0, v[42:43]
	v_lshlrev_b64 v[44:45], 9, v[40:41]
	v_lshl_add_u64 v[44:45], v[14:15], 0, v[44:45]
	v_mov_b32_e32 v46, 0x10000
	v_mov_b32_e32 v47, 0
	v_mov_b32_e32 v48, 0xffff0000
	v_mov_b32_e32 v49, -1
	v_cndmask_b32_e32 v46, v48, v46, vcc
	v_cndmask_b32_e32 v47, v49, v47, vcc
	v_mov_b32_e32 v50, 0x200
	v_mov_b32_e32 v51, 0
	v_mov_b32_e32 v48, 0xfffffe00
	v_cndmask_b32_e32 v50, v48, v50, vcc
	v_cndmask_b32_e32 v51, v49, v51, vcc
	v_mov_b64_e32 v[100:101], v[42:43]
	v_mov_b32_e32 v104, 0
	v_mov_b32_e32 v105, 0
	v_mov_b32_e32 v106, 0
	v_mov_b32_e32 v107, 0
	v_mov_b32_e32 v108, 0
	v_mov_b32_e32 v109, 0
	v_mov_b32_e32 v110, 0
	v_mov_b32_e32 v111, 0
	global_load_dwordx4 v[52:55], v[42:43], off
	global_load_dwordx4 v[56:59], v[44:45], off
	global_load_dwordx4 v[60:63], v[44:45], off offset:16
	v_lshl_add_u64 v[42:43], v[42:43], 0, v[46:47]
	v_lshl_add_u64 v[44:45], v[44:45], 0, v[50:51]
	global_load_dwordx4 v[64:67], v[42:43], off
	global_load_dwordx4 v[68:71], v[44:45], off
	global_load_dwordx4 v[72:75], v[44:45], off offset:16
	v_lshl_add_u64 v[42:43], v[42:43], 0, v[46:47]
	v_lshl_add_u64 v[44:45], v[44:45], 0, v[50:51]
	global_load_dwordx4 v[76:79], v[42:43], off
	global_load_dwordx4 v[80:83], v[44:45], off
	global_load_dwordx4 v[84:87], v[44:45], off offset:16
	v_lshl_add_u64 v[42:43], v[42:43], 0, v[46:47]
	v_lshl_add_u64 v[44:45], v[44:45], 0, v[50:51]
	global_load_dwordx4 v[88:91], v[42:43], off
	global_load_dwordx4 v[92:95], v[44:45], off
	global_load_dwordx4 v[96:99], v[44:45], off offset:16
	v_lshl_add_u64 v[42:43], v[42:43], 0, v[46:47]
	v_lshl_add_u64 v[44:45], v[44:45], 0, v[50:51]
	global_load_dwordx4 v[124:127], v[42:43], off
	global_load_dwordx4 v[128:131], v[44:45], off
	global_load_dwordx4 v[132:135], v[44:45], off offset:16
	v_lshl_add_u64 v[42:43], v[42:43], 0, v[46:47]
	v_lshl_add_u64 v[44:45], v[44:45], 0, v[50:51]
	global_load_dwordx4 v[136:139], v[42:43], off
	global_load_dwordx4 v[140:143], v[44:45], off
	global_load_dwordx4 v[144:147], v[44:45], off offset:16
	v_lshl_add_u64 v[42:43], v[42:43], 0, v[46:47]
	v_lshl_add_u64 v[44:45], v[44:45], 0, v[50:51]
	global_load_dwordx4 v[148:151], v[42:43], off
	global_load_dwordx4 v[152:155], v[44:45], off
	global_load_dwordx4 v[156:159], v[44:45], off offset:16
	v_lshl_add_u64 v[42:43], v[42:43], 0, v[46:47]
	v_lshl_add_u64 v[44:45], v[44:45], 0, v[50:51]
	global_load_dwordx4 v[160:163], v[42:43], off
	global_load_dwordx4 v[164:167], v[44:45], off
	global_load_dwordx4 v[168:171], v[44:45], off offset:16
	v_lshl_add_u64 v[42:43], v[42:43], 0, v[46:47]
	v_lshl_add_u64 v[44:45], v[44:45], 0, v[50:51]
	v_cvt_pk_bf16_f32 v112, v104, v105
	v_cvt_pk_bf16_f32 v113, v106, v107
	v_cvt_pk_bf16_f32 v114, v108, v109
	v_cvt_pk_bf16_f32 v115, v110, v111
	s_waitcnt vmcnt(21)
	global_store_dwordx4 v[100:101], v[112:115], off
	v_lshlrev_b32_e32 v116, 16, v52
	v_and_b32_e32 v117, 0xffff0000, v52
	v_lshlrev_b32_e32 v118, 16, v53
	v_and_b32_e32 v119, 0xffff0000, v53
	v_lshlrev_b32_e32 v120, 16, v54
	v_and_b32_e32 v121, 0xffff0000, v54
	v_lshlrev_b32_e32 v122, 16, v55
	v_and_b32_e32 v123, 0xffff0000, v55
	v_pk_fma_f32 v[104:105], v[104:105], v[56:57], v[116:117]
	v_pk_fma_f32 v[106:107], v[106:107], v[58:59], v[118:119]
	v_pk_fma_f32 v[108:109], v[108:109], v[60:61], v[120:121]
	v_pk_fma_f32 v[110:111], v[110:111], v[62:63], v[122:123]
	v_lshl_add_u64 v[100:101], v[100:101], 0, v[46:47]
	global_load_dwordx4 v[52:55], v[42:43], off
	global_load_dwordx4 v[56:59], v[44:45], off
	global_load_dwordx4 v[60:63], v[44:45], off offset:16
	v_lshl_add_u64 v[42:43], v[42:43], 0, v[46:47]
	v_lshl_add_u64 v[44:45], v[44:45], 0, v[50:51]
	v_cvt_pk_bf16_f32 v112, v104, v105
	v_cvt_pk_bf16_f32 v113, v106, v107
	v_cvt_pk_bf16_f32 v114, v108, v109
	v_cvt_pk_bf16_f32 v115, v110, v111
	s_waitcnt vmcnt(22)
	global_store_dwordx4 v[100:101], v[112:115], off
	v_lshlrev_b32_e32 v116, 16, v64
	v_and_b32_e32 v117, 0xffff0000, v64
	v_lshlrev_b32_e32 v118, 16, v65
	v_and_b32_e32 v119, 0xffff0000, v65
	v_lshlrev_b32_e32 v120, 16, v66
	v_and_b32_e32 v121, 0xffff0000, v66
	v_lshlrev_b32_e32 v122, 16, v67
	v_and_b32_e32 v123, 0xffff0000, v67
	v_pk_fma_f32 v[104:105], v[104:105], v[68:69], v[116:117]
	v_pk_fma_f32 v[106:107], v[106:107], v[70:71], v[118:119]
	v_pk_fma_f32 v[108:109], v[108:109], v[72:73], v[120:121]
	v_pk_fma_f32 v[110:111], v[110:111], v[74:75], v[122:123]
	v_lshl_add_u64 v[100:101], v[100:101], 0, v[46:47]
	global_load_dwordx4 v[64:67], v[42:43], off
	global_load_dwordx4 v[68:71], v[44:45], off
	global_load_dwordx4 v[72:75], v[44:45], off offset:16
	v_lshl_add_u64 v[42:43], v[42:43], 0, v[46:47]
	v_lshl_add_u64 v[44:45], v[44:45], 0, v[50:51]
	v_cvt_pk_bf16_f32 v112, v104, v105
	v_cvt_pk_bf16_f32 v113, v106, v107
	v_cvt_pk_bf16_f32 v114, v108, v109
	v_cvt_pk_bf16_f32 v115, v110, v111
	s_waitcnt vmcnt(23)
	global_store_dwordx4 v[100:101], v[112:115], off
	v_lshlrev_b32_e32 v116, 16, v76
	v_and_b32_e32 v117, 0xffff0000, v76
	v_lshlrev_b32_e32 v118, 16, v77
	v_and_b32_e32 v119, 0xffff0000, v77
	v_lshlrev_b32_e32 v120, 16, v78
	v_and_b32_e32 v121, 0xffff0000, v78
	v_lshlrev_b32_e32 v122, 16, v79
	v_and_b32_e32 v123, 0xffff0000, v79
	v_pk_fma_f32 v[104:105], v[104:105], v[80:81], v[116:117]
	v_pk_fma_f32 v[106:107], v[106:107], v[82:83], v[118:119]
	v_pk_fma_f32 v[108:109], v[108:109], v[84:85], v[120:121]
	v_pk_fma_f32 v[110:111], v[110:111], v[86:87], v[122:123]
	v_lshl_add_u64 v[100:101], v[100:101], 0, v[46:47]
	global_load_dwordx4 v[76:79], v[42:43], off
	global_load_dwordx4 v[80:83], v[44:45], off
	global_load_dwordx4 v[84:87], v[44:45], off offset:16
	v_lshl_add_u64 v[42:43], v[42:43], 0, v[46:47]
	v_lshl_add_u64 v[44:45], v[44:45], 0, v[50:51]
	v_cvt_pk_bf16_f32 v112, v104, v105
	v_cvt_pk_bf16_f32 v113, v106, v107
	v_cvt_pk_bf16_f32 v114, v108, v109
	v_cvt_pk_bf16_f32 v115, v110, v111
	s_waitcnt vmcnt(24)
	global_store_dwordx4 v[100:101], v[112:115], off
	v_lshlrev_b32_e32 v116, 16, v88
	v_and_b32_e32 v117, 0xffff0000, v88
	v_lshlrev_b32_e32 v118, 16, v89
	v_and_b32_e32 v119, 0xffff0000, v89
	v_lshlrev_b32_e32 v120, 16, v90
	v_and_b32_e32 v121, 0xffff0000, v90
	v_lshlrev_b32_e32 v122, 16, v91
	v_and_b32_e32 v123, 0xffff0000, v91
	v_pk_fma_f32 v[104:105], v[104:105], v[92:93], v[116:117]
	v_pk_fma_f32 v[106:107], v[106:107], v[94:95], v[118:119]
	v_pk_fma_f32 v[108:109], v[108:109], v[96:97], v[120:121]
	v_pk_fma_f32 v[110:111], v[110:111], v[98:99], v[122:123]
	v_lshl_add_u64 v[100:101], v[100:101], 0, v[46:47]
	global_load_dwordx4 v[88:91], v[42:43], off
	global_load_dwordx4 v[92:95], v[44:45], off
	global_load_dwordx4 v[96:99], v[44:45], off offset:16
	v_lshl_add_u64 v[42:43], v[42:43], 0, v[46:47]
	v_lshl_add_u64 v[44:45], v[44:45], 0, v[50:51]
	v_cvt_pk_bf16_f32 v112, v104, v105
	v_cvt_pk_bf16_f32 v113, v106, v107
	v_cvt_pk_bf16_f32 v114, v108, v109
	v_cvt_pk_bf16_f32 v115, v110, v111
	s_waitcnt vmcnt(25)
	global_store_dwordx4 v[100:101], v[112:115], off
	v_lshlrev_b32_e32 v116, 16, v124
	v_and_b32_e32 v117, 0xffff0000, v124
	v_lshlrev_b32_e32 v118, 16, v125
	v_and_b32_e32 v119, 0xffff0000, v125
	v_lshlrev_b32_e32 v120, 16, v126
	v_and_b32_e32 v121, 0xffff0000, v126
	v_lshlrev_b32_e32 v122, 16, v127
	v_and_b32_e32 v123, 0xffff0000, v127
	v_pk_fma_f32 v[104:105], v[104:105], v[128:129], v[116:117]
	v_pk_fma_f32 v[106:107], v[106:107], v[130:131], v[118:119]
	v_pk_fma_f32 v[108:109], v[108:109], v[132:133], v[120:121]
	v_pk_fma_f32 v[110:111], v[110:111], v[134:135], v[122:123]
	v_lshl_add_u64 v[100:101], v[100:101], 0, v[46:47]
	global_load_dwordx4 v[124:127], v[42:43], off
	global_load_dwordx4 v[128:131], v[44:45], off
	global_load_dwordx4 v[132:135], v[44:45], off offset:16
	v_lshl_add_u64 v[42:43], v[42:43], 0, v[46:47]
	v_lshl_add_u64 v[44:45], v[44:45], 0, v[50:51]
	v_cvt_pk_bf16_f32 v112, v104, v105
	v_cvt_pk_bf16_f32 v113, v106, v107
	v_cvt_pk_bf16_f32 v114, v108, v109
	v_cvt_pk_bf16_f32 v115, v110, v111
	s_waitcnt vmcnt(26)
	global_store_dwordx4 v[100:101], v[112:115], off
	v_lshlrev_b32_e32 v116, 16, v136
	v_and_b32_e32 v117, 0xffff0000, v136
	v_lshlrev_b32_e32 v118, 16, v137
	v_and_b32_e32 v119, 0xffff0000, v137
	v_lshlrev_b32_e32 v120, 16, v138
	v_and_b32_e32 v121, 0xffff0000, v138
	v_lshlrev_b32_e32 v122, 16, v139
	v_and_b32_e32 v123, 0xffff0000, v139
	v_pk_fma_f32 v[104:105], v[104:105], v[140:141], v[116:117]
	v_pk_fma_f32 v[106:107], v[106:107], v[142:143], v[118:119]
	v_pk_fma_f32 v[108:109], v[108:109], v[144:145], v[120:121]
	v_pk_fma_f32 v[110:111], v[110:111], v[146:147], v[122:123]
	v_lshl_add_u64 v[100:101], v[100:101], 0, v[46:47]
	global_load_dwordx4 v[136:139], v[42:43], off
	global_load_dwordx4 v[140:143], v[44:45], off
	global_load_dwordx4 v[144:147], v[44:45], off offset:16
	v_lshl_add_u64 v[42:43], v[42:43], 0, v[46:47]
	v_lshl_add_u64 v[44:45], v[44:45], 0, v[50:51]
	v_cvt_pk_bf16_f32 v112, v104, v105
	v_cvt_pk_bf16_f32 v113, v106, v107
	v_cvt_pk_bf16_f32 v114, v108, v109
	v_cvt_pk_bf16_f32 v115, v110, v111
	s_waitcnt vmcnt(27)
	global_store_dwordx4 v[100:101], v[112:115], off
	v_lshlrev_b32_e32 v116, 16, v148
	v_and_b32_e32 v117, 0xffff0000, v148
	v_lshlrev_b32_e32 v118, 16, v149
	v_and_b32_e32 v119, 0xffff0000, v149
	v_lshlrev_b32_e32 v120, 16, v150
	v_and_b32_e32 v121, 0xffff0000, v150
	v_lshlrev_b32_e32 v122, 16, v151
	v_and_b32_e32 v123, 0xffff0000, v151
	v_pk_fma_f32 v[104:105], v[104:105], v[152:153], v[116:117]
	v_pk_fma_f32 v[106:107], v[106:107], v[154:155], v[118:119]
	v_pk_fma_f32 v[108:109], v[108:109], v[156:157], v[120:121]
	v_pk_fma_f32 v[110:111], v[110:111], v[158:159], v[122:123]
	v_lshl_add_u64 v[100:101], v[100:101], 0, v[46:47]
	global_load_dwordx4 v[148:151], v[42:43], off
	global_load_dwordx4 v[152:155], v[44:45], off
	global_load_dwordx4 v[156:159], v[44:45], off offset:16
	v_lshl_add_u64 v[42:43], v[42:43], 0, v[46:47]
	v_lshl_add_u64 v[44:45], v[44:45], 0, v[50:51]
	v_cvt_pk_bf16_f32 v112, v104, v105
	v_cvt_pk_bf16_f32 v113, v106, v107
	v_cvt_pk_bf16_f32 v114, v108, v109
	v_cvt_pk_bf16_f32 v115, v110, v111
	s_waitcnt vmcnt(28)
	global_store_dwordx4 v[100:101], v[112:115], off
	v_lshlrev_b32_e32 v116, 16, v160
	v_and_b32_e32 v117, 0xffff0000, v160
	v_lshlrev_b32_e32 v118, 16, v161
	v_and_b32_e32 v119, 0xffff0000, v161
	v_lshlrev_b32_e32 v120, 16, v162
	v_and_b32_e32 v121, 0xffff0000, v162
	v_lshlrev_b32_e32 v122, 16, v163
	v_and_b32_e32 v123, 0xffff0000, v163
	v_pk_fma_f32 v[104:105], v[104:105], v[164:165], v[116:117]
	v_pk_fma_f32 v[106:107], v[106:107], v[166:167], v[118:119]
	v_pk_fma_f32 v[108:109], v[108:109], v[168:169], v[120:121]
	v_pk_fma_f32 v[110:111], v[110:111], v[170:171], v[122:123]
	v_lshl_add_u64 v[100:101], v[100:101], 0, v[46:47]
	global_load_dwordx4 v[160:163], v[42:43], off
	global_load_dwordx4 v[164:167], v[44:45], off
	global_load_dwordx4 v[168:171], v[44:45], off offset:16
	v_lshl_add_u64 v[42:43], v[42:43], 0, v[46:47]
	v_lshl_add_u64 v[44:45], v[44:45], 0, v[50:51]
	s_mov_b32 s7, 3
.Lscan_pipe:
	v_cvt_pk_bf16_f32 v112, v104, v105
	v_cvt_pk_bf16_f32 v113, v106, v107
	v_cvt_pk_bf16_f32 v114, v108, v109
	v_cvt_pk_bf16_f32 v115, v110, v111
	s_waitcnt vmcnt(28)
	global_store_dwordx4 v[100:101], v[112:115], off
	v_lshlrev_b32_e32 v116, 16, v52
	v_and_b32_e32 v117, 0xffff0000, v52
	v_lshlrev_b32_e32 v118, 16, v53
	v_and_b32_e32 v119, 0xffff0000, v53
	v_lshlrev_b32_e32 v120, 16, v54
	v_and_b32_e32 v121, 0xffff0000, v54
	v_lshlrev_b32_e32 v122, 16, v55
	v_and_b32_e32 v123, 0xffff0000, v55
	v_pk_fma_f32 v[104:105], v[104:105], v[56:57], v[116:117]
	v_pk_fma_f32 v[106:107], v[106:107], v[58:59], v[118:119]
	v_pk_fma_f32 v[108:109], v[108:109], v[60:61], v[120:121]
	v_pk_fma_f32 v[110:111], v[110:111], v[62:63], v[122:123]
	v_lshl_add_u64 v[100:101], v[100:101], 0, v[46:47]
	global_load_dwordx4 v[52:55], v[42:43], off
	global_load_dwordx4 v[56:59], v[44:45], off
	global_load_dwordx4 v[60:63], v[44:45], off offset:16
	v_lshl_add_u64 v[42:43], v[42:43], 0, v[46:47]
	v_lshl_add_u64 v[44:45], v[44:45], 0, v[50:51]
	v_cvt_pk_bf16_f32 v112, v104, v105
	v_cvt_pk_bf16_f32 v113, v106, v107
	v_cvt_pk_bf16_f32 v114, v108, v109
	v_cvt_pk_bf16_f32 v115, v110, v111
	s_waitcnt vmcnt(28)
	global_store_dwordx4 v[100:101], v[112:115], off
	v_lshlrev_b32_e32 v116, 16, v64
	v_and_b32_e32 v117, 0xffff0000, v64
	v_lshlrev_b32_e32 v118, 16, v65
	v_and_b32_e32 v119, 0xffff0000, v65
	v_lshlrev_b32_e32 v120, 16, v66
	v_and_b32_e32 v121, 0xffff0000, v66
	v_lshlrev_b32_e32 v122, 16, v67
	v_and_b32_e32 v123, 0xffff0000, v67
	v_pk_fma_f32 v[104:105], v[104:105], v[68:69], v[116:117]
	v_pk_fma_f32 v[106:107], v[106:107], v[70:71], v[118:119]
	v_pk_fma_f32 v[108:109], v[108:109], v[72:73], v[120:121]
	v_pk_fma_f32 v[110:111], v[110:111], v[74:75], v[122:123]
	v_lshl_add_u64 v[100:101], v[100:101], 0, v[46:47]
	global_load_dwordx4 v[64:67], v[42:43], off
	global_load_dwordx4 v[68:71], v[44:45], off
	global_load_dwordx4 v[72:75], v[44:45], off offset:16
	v_lshl_add_u64 v[42:43], v[42:43], 0, v[46:47]
	v_lshl_add_u64 v[44:45], v[44:45], 0, v[50:51]
	v_cvt_pk_bf16_f32 v112, v104, v105
	v_cvt_pk_bf16_f32 v113, v106, v107
	v_cvt_pk_bf16_f32 v114, v108, v109
	v_cvt_pk_bf16_f32 v115, v110, v111
	s_waitcnt vmcnt(28)
	global_store_dwordx4 v[100:101], v[112:115], off
	v_lshlrev_b32_e32 v116, 16, v76
	v_and_b32_e32 v117, 0xffff0000, v76
	v_lshlrev_b32_e32 v118, 16, v77
	v_and_b32_e32 v119, 0xffff0000, v77
	v_lshlrev_b32_e32 v120, 16, v78
	v_and_b32_e32 v121, 0xffff0000, v78
	v_lshlrev_b32_e32 v122, 16, v79
	v_and_b32_e32 v123, 0xffff0000, v79
	v_pk_fma_f32 v[104:105], v[104:105], v[80:81], v[116:117]
	v_pk_fma_f32 v[106:107], v[106:107], v[82:83], v[118:119]
	v_pk_fma_f32 v[108:109], v[108:109], v[84:85], v[120:121]
	v_pk_fma_f32 v[110:111], v[110:111], v[86:87], v[122:123]
	v_lshl_add_u64 v[100:101], v[100:101], 0, v[46:47]
	global_load_dwordx4 v[76:79], v[42:43], off
	global_load_dwordx4 v[80:83], v[44:45], off
	global_load_dwordx4 v[84:87], v[44:45], off offset:16
	v_lshl_add_u64 v[42:43], v[42:43], 0, v[46:47]
	v_lshl_add_u64 v[44:45], v[44:45], 0, v[50:51]
	v_cvt_pk_bf16_f32 v112, v104, v105
	v_cvt_pk_bf16_f32 v113, v106, v107
	v_cvt_pk_bf16_f32 v114, v108, v109
	v_cvt_pk_bf16_f32 v115, v110, v111
	s_waitcnt vmcnt(28)
	global_store_dwordx4 v[100:101], v[112:115], off
	v_lshlrev_b32_e32 v116, 16, v88
	v_and_b32_e32 v117, 0xffff0000, v88
	v_lshlrev_b32_e32 v118, 16, v89
	v_and_b32_e32 v119, 0xffff0000, v89
	v_lshlrev_b32_e32 v120, 16, v90
	v_and_b32_e32 v121, 0xffff0000, v90
	v_lshlrev_b32_e32 v122, 16, v91
	v_and_b32_e32 v123, 0xffff0000, v91
	v_pk_fma_f32 v[104:105], v[104:105], v[92:93], v[116:117]
	v_pk_fma_f32 v[106:107], v[106:107], v[94:95], v[118:119]
	v_pk_fma_f32 v[108:109], v[108:109], v[96:97], v[120:121]
	v_pk_fma_f32 v[110:111], v[110:111], v[98:99], v[122:123]
	v_lshl_add_u64 v[100:101], v[100:101], 0, v[46:47]
	global_load_dwordx4 v[88:91], v[42:43], off
	global_load_dwordx4 v[92:95], v[44:45], off
	global_load_dwordx4 v[96:99], v[44:45], off offset:16
	v_lshl_add_u64 v[42:43], v[42:43], 0, v[46:47]
	v_lshl_add_u64 v[44:45], v[44:45], 0, v[50:51]
	v_cvt_pk_bf16_f32 v112, v104, v105
	v_cvt_pk_bf16_f32 v113, v106, v107
	v_cvt_pk_bf16_f32 v114, v108, v109
	v_cvt_pk_bf16_f32 v115, v110, v111
	s_waitcnt vmcnt(28)
	global_store_dwordx4 v[100:101], v[112:115], off
	v_lshlrev_b32_e32 v116, 16, v124
	v_and_b32_e32 v117, 0xffff0000, v124
	v_lshlrev_b32_e32 v118, 16, v125
	v_and_b32_e32 v119, 0xffff0000, v125
	v_lshlrev_b32_e32 v120, 16, v126
	v_and_b32_e32 v121, 0xffff0000, v126
	v_lshlrev_b32_e32 v122, 16, v127
	v_and_b32_e32 v123, 0xffff0000, v127
	v_pk_fma_f32 v[104:105], v[104:105], v[128:129], v[116:117]
	v_pk_fma_f32 v[106:107], v[106:107], v[130:131], v[118:119]
	v_pk_fma_f32 v[108:109], v[108:109], v[132:133], v[120:121]
	v_pk_fma_f32 v[110:111], v[110:111], v[134:135], v[122:123]
	v_lshl_add_u64 v[100:101], v[100:101], 0, v[46:47]
	global_load_dwordx4 v[124:127], v[42:43], off
	global_load_dwordx4 v[128:131], v[44:45], off
	global_load_dwordx4 v[132:135], v[44:45], off offset:16
	v_lshl_add_u64 v[42:43], v[42:43], 0, v[46:47]
	v_lshl_add_u64 v[44:45], v[44:45], 0, v[50:51]
	v_cvt_pk_bf16_f32 v112, v104, v105
	v_cvt_pk_bf16_f32 v113, v106, v107
	v_cvt_pk_bf16_f32 v114, v108, v109
	v_cvt_pk_bf16_f32 v115, v110, v111
	s_waitcnt vmcnt(28)
	global_store_dwordx4 v[100:101], v[112:115], off
	v_lshlrev_b32_e32 v116, 16, v136
	v_and_b32_e32 v117, 0xffff0000, v136
	v_lshlrev_b32_e32 v118, 16, v137
	v_and_b32_e32 v119, 0xffff0000, v137
	v_lshlrev_b32_e32 v120, 16, v138
	v_and_b32_e32 v121, 0xffff0000, v138
	v_lshlrev_b32_e32 v122, 16, v139
	v_and_b32_e32 v123, 0xffff0000, v139
	v_pk_fma_f32 v[104:105], v[104:105], v[140:141], v[116:117]
	v_pk_fma_f32 v[106:107], v[106:107], v[142:143], v[118:119]
	v_pk_fma_f32 v[108:109], v[108:109], v[144:145], v[120:121]
	v_pk_fma_f32 v[110:111], v[110:111], v[146:147], v[122:123]
	v_lshl_add_u64 v[100:101], v[100:101], 0, v[46:47]
	global_load_dwordx4 v[136:139], v[42:43], off
	global_load_dwordx4 v[140:143], v[44:45], off
	global_load_dwordx4 v[144:147], v[44:45], off offset:16
	v_lshl_add_u64 v[42:43], v[42:43], 0, v[46:47]
	v_lshl_add_u64 v[44:45], v[44:45], 0, v[50:51]
	v_cvt_pk_bf16_f32 v112, v104, v105
	v_cvt_pk_bf16_f32 v113, v106, v107
	v_cvt_pk_bf16_f32 v114, v108, v109
	v_cvt_pk_bf16_f32 v115, v110, v111
	s_waitcnt vmcnt(28)
	global_store_dwordx4 v[100:101], v[112:115], off
	v_lshlrev_b32_e32 v116, 16, v148
	v_and_b32_e32 v117, 0xffff0000, v148
	v_lshlrev_b32_e32 v118, 16, v149
	v_and_b32_e32 v119, 0xffff0000, v149
	v_lshlrev_b32_e32 v120, 16, v150
	v_and_b32_e32 v121, 0xffff0000, v150
	v_lshlrev_b32_e32 v122, 16, v151
	v_and_b32_e32 v123, 0xffff0000, v151
	v_pk_fma_f32 v[104:105], v[104:105], v[152:153], v[116:117]
	v_pk_fma_f32 v[106:107], v[106:107], v[154:155], v[118:119]
	v_pk_fma_f32 v[108:109], v[108:109], v[156:157], v[120:121]
	v_pk_fma_f32 v[110:111], v[110:111], v[158:159], v[122:123]
	v_lshl_add_u64 v[100:101], v[100:101], 0, v[46:47]
	global_load_dwordx4 v[148:151], v[42:43], off
	global_load_dwordx4 v[152:155], v[44:45], off
	global_load_dwordx4 v[156:159], v[44:45], off offset:16
	v_lshl_add_u64 v[42:43], v[42:43], 0, v[46:47]
	v_lshl_add_u64 v[44:45], v[44:45], 0, v[50:51]
	v_cvt_pk_bf16_f32 v112, v104, v105
	v_cvt_pk_bf16_f32 v113, v106, v107
	v_cvt_pk_bf16_f32 v114, v108, v109
	v_cvt_pk_bf16_f32 v115, v110, v111
	s_waitcnt vmcnt(28)
	global_store_dwordx4 v[100:101], v[112:115], off
	v_lshlrev_b32_e32 v116, 16, v160
	v_and_b32_e32 v117, 0xffff0000, v160
	v_lshlrev_b32_e32 v118, 16, v161
	v_and_b32_e32 v119, 0xffff0000, v161
	v_lshlrev_b32_e32 v120, 16, v162
	v_and_b32_e32 v121, 0xffff0000, v162
	v_lshlrev_b32_e32 v122, 16, v163
	v_and_b32_e32 v123, 0xffff0000, v163
	v_pk_fma_f32 v[104:105], v[104:105], v[164:165], v[116:117]
	v_pk_fma_f32 v[106:107], v[106:107], v[166:167], v[118:119]
	v_pk_fma_f32 v[108:109], v[108:109], v[168:169], v[120:121]
	v_pk_fma_f32 v[110:111], v[110:111], v[170:171], v[122:123]
	v_lshl_add_u64 v[100:101], v[100:101], 0, v[46:47]
	global_load_dwordx4 v[160:163], v[42:43], off
	global_load_dwordx4 v[164:167], v[44:45], off
	global_load_dwordx4 v[168:171], v[44:45], off offset:16
	v_lshl_add_u64 v[42:43], v[42:43], 0, v[46:47]
	v_lshl_add_u64 v[44:45], v[44:45], 0, v[50:51]
	s_sub_i32 s7, s7, 1
	s_cmp_lg_u32 s7, 0
	s_cbranch_scc1 .Lscan_pipe
	v_add_u32_e32 v28, s77, v28
	v_cmp_lt_i32_e32 vcc, s6, v28
	s_or_b64 s[4:5], vcc, s[4:5]
	s_andn2_b64 exec, exec, s[4:5]
	s_cbranch_execnz .LBB0_555
